# context k|v projection split over 32 workgroups: each runs one 128-row half of a tile (the other wave half only stages and joins barriers); tail copies on the remaining 224
# baseline (speedup 1.0000x reference)
;     __host__ __device__ bool next(int i, Unit& u) const { const long L = (long)i * G + c; if (L >= nwg) return false; u.pm = 0; u.pn = c % nN; return true; }
;     __host__ __device__ bool next(int i, Unit& u) const {
;         const long L = (long)i * G + c; if (L >= nwg) return false;
;         int wgid = (int)L; { const int q = nwg / NXCD, r = nwg % NXCD, xcd = wgid % NXCD, off = wgid / NXCD; wgid = (xcd < r ? xcd * (q + 1) : r * (q + 1) + (xcd - r) * q) + off; }
;         const int nig = WGM * nN, gid = wgid / nig, fm = gid * WGM, gsz = (nM - fm) < WGM ? (nM - fm) : WGM;
;         u.pm = fm + ((wgid % nig) % gsz); u.pn = (wgid % nig) / gsz; return true;
; template <class Epi, class Sched, bool ALIGN_EPI = false, bool SP2 = false, bool F8 = false>
; __device__ __forceinline__ void gemm_phase(PG8_LAS unsigned char* lds, const Gemm g, const Sched& S, const Epi& E) {
;     ...
;     Unit cur, nxt; int ui = 0;
;     if (!S.next(0, cur)) return;
.LBB0_272:
	s_cmp_lt_i32 s2, 32
	s_cselect_b64 s[4:5], -1, 0
	s_cmp_gt_i32 s2, 31
	v_readfirstlane_b32 s12, v0
	s_cbranch_scc1 .LBB0_278
	s_lshr_b32 s7, s2, 1
	s_ashr_i32 s6, s7, 31
	s_lshr_b32 s6, s6, 29
	s_add_i32 s8, s7, s6
	s_and_b32 s6, s8, -8
	s_sub_i32 s9, s7, s6
	s_cmp_gt_i32 s9, -1
	s_cbranch_scc0 .LBB0_275
	s_lshl_b32 s10, s9, 1
	s_cbranch_execz .LBB0_276
	s_branch .LBB0_277

; template <class Epi, class Sched, bool ALIGN_EPI = false, bool SP2 = false, bool F8 = false>
; __device__ __forceinline__ void gemm_phase(PG8_LAS unsigned char* lds, const Gemm g, const Sched& S, const Epi& E) {
;     ...
;     f32x4 acc[2][2][4][2];
; #pragma unroll
;     for (int a = 0; a < 2; ++a)
; #pragma unroll
;         for (int b = 0; b < 2; ++b)
; #pragma unroll
;             for (int m = 0; m < 4; ++m)
; #pragma unroll
;                 for (int n = 0; n < 2; ++n) acc[a][b][m][n] = (f32x4){0.f, 0.f, 0.f, 0.f};
;     bf16x8 At[4][2], B0[2][2], B1[2][2];
;     const char* cA = PG8_ABASE(cur.pm); const char* cB = (const char*)g.Bt + (size_t)cur.pn * tstep;
.LBB0_290:
	s_ashr_i32 s65, s64, 31
	s_lshl_b64 s[24:25], s[64:65], 19
	s_add_u32 s66, s15, s24
	s_addc_u32 s67, s23, s25
	s_and_b64 s[24:25], s[54:55], exec
	s_cselect_b32 s7, s67, s73
	s_cselect_b32 s65, s66, s72
	s_ashr_i32 s63, s62, 31
	s_lshl_b64 s[24:25], s[62:63], 19
	s_add_u32 s68, s50, s24
	s_addc_u32 s69, s51, s25
	s_and_b64 s[24:25], s[54:55], exec
	s_cselect_b32 s63, s69, s75
	s_cselect_b32 s71, s68, s74
	s_add_u32 s72, s72, 0x40080
	s_addc_u32 s73, s73, 0
	s_add_u32 s85, s74, 0x100
	v_mov_b32_e32 v34, 0
	s_addc_u32 s86, s75, 0
	s_mov_b32 s87, -2
	v_mov_b32_e32 v35, 0
	v_pk_mul_f32 v[36:37], v[34:35], v[34:35]
	v_pk_mul_f32 v[38:39], v[34:35], v[34:35]
	v_pk_mul_f32 v[40:41], v[34:35], v[34:35]
	v_pk_mul_f32 v[42:43], v[34:35], v[34:35]
	v_pk_mul_f32 v[44:45], v[34:35], v[34:35]
	v_pk_mul_f32 v[46:47], v[34:35], v[34:35]
	v_pk_mul_f32 v[48:49], v[34:35], v[34:35]
	v_pk_mul_f32 v[50:51], v[34:35], v[34:35]
	v_pk_mul_f32 v[52:53], v[34:35], v[34:35]
	v_pk_mul_f32 v[54:55], v[34:35], v[34:35]
	v_pk_mul_f32 v[56:57], v[34:35], v[34:35]
	v_pk_mul_f32 v[58:59], v[34:35], v[34:35]
	v_pk_mul_f32 v[60:61], v[34:35], v[34:35]
	v_pk_mul_f32 v[62:63], v[34:35], v[34:35]
	v_pk_mul_f32 v[64:65], v[34:35], v[34:35]
	v_pk_mul_f32 v[66:67], v[34:35], v[34:35]
	v_pk_mul_f32 v[68:69], v[34:35], v[34:35]
	v_pk_mul_f32 v[70:71], v[34:35], v[34:35]
	v_pk_mul_f32 v[72:73], v[34:35], v[34:35]
	v_pk_mul_f32 v[74:75], v[34:35], v[34:35]
	v_pk_mul_f32 v[76:77], v[34:35], v[34:35]
	v_pk_mul_f32 v[78:79], v[34:35], v[34:35]
	v_pk_mul_f32 v[80:81], v[34:35], v[34:35]
	v_pk_mul_f32 v[82:83], v[34:35], v[34:35]
	v_pk_mul_f32 v[84:85], v[34:35], v[34:35]
	v_pk_mul_f32 v[86:87], v[34:35], v[34:35]
	v_pk_mul_f32 v[88:89], v[34:35], v[34:35]
	v_pk_mul_f32 v[90:91], v[34:35], v[34:35]
	v_pk_mul_f32 v[92:93], v[34:35], v[34:35]
	v_pk_mul_f32 v[94:95], v[34:35], v[34:35]
	v_pk_mul_f32 v[96:97], v[34:35], v[34:35]
	v_pk_mul_f32 v[98:99], v[34:35], v[34:35]
	v_pk_mul_f32 v[100:101], v[34:35], v[34:35]
	v_pk_mul_f32 v[102:103], v[34:35], v[34:35]
	v_pk_mul_f32 v[104:105], v[34:35], v[34:35]
	v_pk_mul_f32 v[106:107], v[34:35], v[34:35]
	v_pk_mul_f32 v[108:109], v[34:35], v[34:35]
	v_pk_mul_f32 v[110:111], v[34:35], v[34:35]
	v_pk_mul_f32 v[112:113], v[34:35], v[34:35]
	v_pk_mul_f32 v[114:115], v[34:35], v[34:35]
	v_pk_mul_f32 v[116:117], v[34:35], v[34:35]
	v_pk_mul_f32 v[118:119], v[34:35], v[34:35]
	v_pk_mul_f32 v[120:121], v[34:35], v[34:35]
	v_pk_mul_f32 v[122:123], v[34:35], v[34:35]
	v_pk_mul_f32 v[124:125], v[34:35], v[34:35]
	v_pk_mul_f32 v[126:127], v[34:35], v[34:35]
	v_pk_mul_f32 v[128:129], v[34:35], v[34:35]
	v_pk_mul_f32 v[130:131], v[34:35], v[34:35]
	v_pk_mul_f32 v[132:133], v[34:35], v[34:35]
	v_pk_mul_f32 v[134:135], v[34:35], v[34:35]
	v_pk_mul_f32 v[136:137], v[34:35], v[34:35]
	v_pk_mul_f32 v[138:139], v[34:35], v[34:35]
	v_pk_mul_f32 v[140:141], v[34:35], v[34:35]
	v_pk_mul_f32 v[142:143], v[34:35], v[34:35]
	v_pk_mul_f32 v[144:145], v[34:35], v[34:35]
	v_pk_mul_f32 v[146:147], v[34:35], v[34:35]
	v_pk_mul_f32 v[148:149], v[34:35], v[34:35]
	v_pk_mul_f32 v[150:151], v[34:35], v[34:35]
	v_pk_mul_f32 v[152:153], v[34:35], v[34:35]
	v_pk_mul_f32 v[154:155], v[34:35], v[34:35]
	v_pk_mul_f32 v[156:157], v[34:35], v[34:35]
	v_pk_mul_f32 v[158:159], v[34:35], v[34:35]
	v_pk_mul_f32 v[160:161], v[34:35], v[34:35]
	s_bitcmp1_b32 s2, 0
	s_cbranch_scc1 .Lk1_h1
	s_cmp_lg_u64 s[8:9], 0
	s_cbranch_scc1 .Lk1_Yi

; #define PG8_STAGE(bufoff, gbase, voff) do { _Pragma("unroll") for (int _i = 0; _i < 2; ++_i) \
;         __builtin_amdgcn_global_load_lds((const unsigned*)((const char*)(gbase) + (voff)[_i]), (PG8_LAS unsigned*)(lds + (bufoff) + ldsw + _i * 8192), 16, 0, 0); } while (0)
; #define PG8_LDA(dst, b, h) do { _Pragma("unroll") for (int m = 0; m < 4; ++m) _Pragma("unroll") for (int k = 0; k < 2; ++k) dst[m][k] = *(const PG8_LAS bf16x8*)(lds + PG8_SA(b, h) + aoff + m * 2048 + k * 1024); } while (0)
; #define PG8_LDB(dst, b, h) do { _Pragma("unroll") for (int n = 0; n < 2; ++n) _Pragma("unroll") for (int k = 0; k < 2; ++k) dst[n][k] = *(const PG8_LAS bf16x8*)(lds + PG8_SB(b, h) + boff + n * 2048 + k * 1024); } while (0)
; #define PG8_WAIT_V(n) asm volatile("s_waitcnt vmcnt(" #n ")" ::: "memory")
; #define PG8_WAIT_L(n) asm volatile("s_waitcnt lgkmcnt(" #n ")" ::: "memory")
; #define PG8_BAR __builtin_amdgcn_s_barrier()
; #define PG8_SCHED __builtin_amdgcn_sched_barrier(0)
; template <class Epi, class Sched, bool ALIGN_EPI = false, bool SP2 = false, bool F8 = false>
; __device__ __forceinline__ void gemm_phase(PG8_LAS unsigned char* lds, const Gemm g, const Sched& S, const Epi& E) {
;     ...
;             PG8_LDB(B0, 0, 0); PG8_LDB(B1, 0, 1); PG8_SCHED; PG8_LDA(At, 0, 0); PG8_STAGE(PG8_SA(1, 1), a1 + hstepA, voffA);
;             PG8_WAIT_V(8); PG8_WAIT_L(0); PG8_BAR; PG8_MMA(0, 0, At, B0); PG8_MMA(0, 1, At, B1); PG8_BAR; PG8_SCHED;
;             PG8_LDA(At, 0, 1); PG8_STAGE(PG8_SB(0, 0), b2, voffB); PG8_STAGE(PG8_SB(0, 1), b2 + hstep, voffB); PG8_STAGE(PG8_SA(0, 0), a2, voffA);
;             PG8_WAIT_V(8); PG8_WAIT_L(0); PG8_BAR; PG8_MMA(1, 0, At, B0); PG8_MMA(1, 1, At, B1); PG8_BAR; PG8_SCHED;
;             PG8_LDB(B0, 1, 0); PG8_LDB(B1, 1, 1); PG8_SCHED; PG8_LDA(At, 1, 0); PG8_STAGE(PG8_SA(0, 1), a2 + hstepA, voffA);
;             PG8_WAIT_V(8); PG8_WAIT_L(0); PG8_BAR; PG8_MMA(0, 0, At, B0); PG8_MMA(0, 1, At, B1); PG8_BAR; PG8_SCHED;
.Lk1_Y:
	ds_read_b128 v[26:29], v195
	ds_read_b128 v[30:33], v195 offset:1024
	ds_read_b128 v[18:21], v195 offset:2048
	ds_read_b128 v[22:25], v195 offset:3072
	ds_read_b128 v[10:13], v196
	ds_read_b128 v[14:17], v196 offset:1024
	ds_read_b128 v[2:5], v196 offset:2048
	ds_read_b128 v[6:9], v196 offset:3072
	s_add_u32 s24, s72, 0xfffc0080
	s_addc_u32 s25, s73, -1
	s_cmp_eq_u32 s87, 12
	s_cselect_b32 s77, s7, s25
	s_cselect_b32 s76, s65, s24
	s_cselect_b32 s75, s63, s86
	s_cselect_b32 s74, s71, s85
	s_add_i32 m0, s26, 0xc000
	ds_read_b128 v[182:185], v197
	ds_read_b128 v[186:189], v197 offset:1024
	ds_read_b128 v[200:203], v197 offset:2048
	ds_read_b128 v[204:207], v197 offset:3072
	ds_read_b128 v[208:211], v197 offset:4096
	ds_read_b128 v[212:215], v197 offset:5120
	ds_read_b128 v[218:221], v197 offset:6144
	ds_read_b128 v[222:225], v197 offset:7168
	global_load_lds_dwordx4 v178, s[72:73]
	s_add_i32 m0, s26, 0xe000
	s_nop 0
	global_load_lds_dwordx4 v180, s[72:73]
	s_waitcnt vmcnt(8)
	s_waitcnt lgkmcnt(0)
	s_barrier
	s_setprio 3
	s_waitcnt lgkmcnt(0)
	v_mfma_f32_16x16x128_f8f6f4 v[158:161], v[26:33], v[182:189], v[158:161]
	v_mfma_f32_16x16x128_f8f6f4 v[154:157], v[18:25], v[182:189], v[154:157]
	v_mfma_f32_16x16x128_f8f6f4 v[142:145], v[26:33], v[200:207], v[142:145]
	v_mfma_f32_16x16x128_f8f6f4 v[138:141], v[18:25], v[200:207], v[138:141]
	v_mfma_f32_16x16x128_f8f6f4 v[126:129], v[26:33], v[208:215], v[126:129]
	v_mfma_f32_16x16x128_f8f6f4 v[122:125], v[18:25], v[208:215], v[122:125]
	v_mfma_f32_16x16x128_f8f6f4 v[110:113], v[26:33], v[218:225], v[110:113]
	v_mfma_f32_16x16x128_f8f6f4 v[106:109], v[18:25], v[218:225], v[106:109]
	s_setprio 0
	s_setprio 3
	v_mfma_f32_16x16x128_f8f6f4 v[150:153], v[10:17], v[182:189], v[150:153]
	v_mfma_f32_16x16x128_f8f6f4 v[146:149], v[2:9], v[182:189], v[146:149]
	v_mfma_f32_16x16x128_f8f6f4 v[134:137], v[10:17], v[200:207], v[134:137]
	v_mfma_f32_16x16x128_f8f6f4 v[130:133], v[2:9], v[200:207], v[130:133]
	v_mfma_f32_16x16x128_f8f6f4 v[118:121], v[10:17], v[208:215], v[118:121]
	v_mfma_f32_16x16x128_f8f6f4 v[114:117], v[2:9], v[208:215], v[114:117]
	v_mfma_f32_16x16x128_f8f6f4 v[102:105], v[10:17], v[218:225], v[102:105]
	v_mfma_f32_16x16x128_f8f6f4 v[98:101], v[2:9], v[218:225], v[98:101]
	s_setprio 0
	s_add_i32 s24, s81, s14
	s_mov_b32 m0, s24
	ds_read_b128 v[200:203], v197 offset:16384
	ds_read_b128 v[204:207], v197 offset:17408
	ds_read_b128 v[208:211], v197 offset:18432
	ds_read_b128 v[212:215], v197 offset:19456
	ds_read_b128 v[218:221], v197 offset:20480
	ds_read_b128 v[222:225], v197 offset:21504
	ds_read_b128 v[226:229], v197 offset:22528
	ds_read_b128 v[230:233], v197 offset:23552
	global_load_lds_dwordx4 v166, s[74:75]
	s_add_i32 m0, s24, 0x2000
	s_add_u32 s24, s74, 0x40000
	s_addc_u32 s25, s75, 0
	s_add_i32 s36, s82, s14
	global_load_lds_dwordx4 v170, s[74:75]
	s_mov_b32 m0, s36
	s_nop 0
	global_load_lds_dwordx4 v166, s[24:25]
	s_add_i32 m0, s36, 0x2000
	s_nop 0
	global_load_lds_dwordx4 v170, s[24:25]
	s_mov_b32 m0, s26
	s_nop 0
	global_load_lds_dwordx4 v164, s[76:77]
	s_mov_b32 m0, s27
	s_nop 0
	global_load_lds_dwordx4 v168, s[76:77]
	s_waitcnt vmcnt(8)
	s_waitcnt lgkmcnt(0)
	s_barrier
	s_setprio 3
	s_waitcnt lgkmcnt(0)
	v_mfma_f32_16x16x128_f8f6f4 v[94:97], v[26:33], v[200:207], v[94:97]
	v_mfma_f32_16x16x128_f8f6f4 v[90:93], v[18:25], v[200:207], v[90:93]
	v_mfma_f32_16x16x128_f8f6f4 v[78:81], v[26:33], v[208:215], v[78:81]
	v_mfma_f32_16x16x128_f8f6f4 v[74:77], v[18:25], v[208:215], v[74:77]
	v_mfma_f32_16x16x128_f8f6f4 v[62:65], v[26:33], v[218:225], v[62:65]
	v_mfma_f32_16x16x128_f8f6f4 v[58:61], v[18:25], v[218:225], v[58:61]
	v_mfma_f32_16x16x128_f8f6f4 v[46:49], v[26:33], v[226:233], v[46:49]
	v_mfma_f32_16x16x128_f8f6f4 v[42:45], v[18:25], v[226:233], v[42:45]
	s_setprio 0
	s_setprio 3
	v_mfma_f32_16x16x128_f8f6f4 v[86:89], v[10:17], v[200:207], v[86:89]
	v_mfma_f32_16x16x128_f8f6f4 v[82:85], v[2:9], v[200:207], v[82:85]
	v_mfma_f32_16x16x128_f8f6f4 v[70:73], v[10:17], v[208:215], v[70:73]
	v_mfma_f32_16x16x128_f8f6f4 v[66:69], v[2:9], v[208:215], v[66:69]
	v_mfma_f32_16x16x128_f8f6f4 v[54:57], v[10:17], v[218:225], v[54:57]
	v_mfma_f32_16x16x128_f8f6f4 v[50:53], v[2:9], v[218:225], v[50:53]
	v_mfma_f32_16x16x128_f8f6f4 v[38:41], v[10:17], v[226:233], v[38:41]
	v_mfma_f32_16x16x128_f8f6f4 v[34:37], v[2:9], v[226:233], v[34:37]
	s_setprio 0
	s_add_i32 s36, 0, 0x18000
	s_add_i32 s37, 0, 0x1c000
	v_add_u32_e32 v14, s36, v190
	v_add_u32_e32 v30, s37, v190
	ds_read_b128 v[2:5], v14
	ds_read_b128 v[6:9], v14 offset:1024
	ds_read_b128 v[10:13], v14 offset:2048
	ds_read_b128 v[14:17], v14 offset:3072
	ds_read_b128 v[18:21], v30
	ds_read_b128 v[22:25], v30 offset:1024
	ds_read_b128 v[26:29], v30 offset:2048
	ds_read_b128 v[30:33], v30 offset:3072
	s_add_u32 s24, s76, 0x40000
	s_addc_u32 s25, s77, 0
	s_mov_b32 m0, s28
	ds_read_b128 v[200:203], v197 offset:32768
	ds_read_b128 v[204:207], v197 offset:33792
	ds_read_b128 v[208:211], v197 offset:34816
	ds_read_b128 v[212:215], v197 offset:35840
	ds_read_b128 v[218:221], v197 offset:36864
	ds_read_b128 v[222:225], v197 offset:37888
	ds_read_b128 v[226:229], v197 offset:38912
	ds_read_b128 v[230:233], v197 offset:39936
	global_load_lds_dwordx4 v164, s[24:25]
	s_mov_b32 m0, s29
	s_nop 0
	global_load_lds_dwordx4 v168, s[24:25]
	s_waitcnt vmcnt(8)
	s_waitcnt lgkmcnt(0)
	s_barrier
; #define PG8_STAGE(bufoff, gbase, voff) do { _Pragma("unroll") for (int _i = 0; _i < 2; ++_i) \
;         __builtin_amdgcn_global_load_lds((const unsigned*)((const char*)(gbase) + (voff)[_i]), (PG8_LAS unsigned*)(lds + (bufoff) + ldsw + _i * 8192), 16, 0, 0); } while (0)
; #define PG8_LDA(dst, b, h) do { _Pragma("unroll") for (int m = 0; m < 4; ++m) _Pragma("unroll") for (int k = 0; k < 2; ++k) dst[m][k] = *(const PG8_LAS bf16x8*)(lds + PG8_SA(b, h) + aoff + m * 2048 + k * 1024); } while (0)
; #define PG8_WAIT_V(n) asm volatile("s_waitcnt vmcnt(" #n ")" ::: "memory")
; #define PG8_WAIT_L(n) asm volatile("s_waitcnt lgkmcnt(" #n ")" ::: "memory")
; #define PG8_BAR __builtin_amdgcn_s_barrier()
; #define PG8_SCHED __builtin_amdgcn_sched_barrier(0)
; template <class Epi, class Sched, bool ALIGN_EPI = false, bool SP2 = false, bool F8 = false>
; __device__ __forceinline__ void gemm_phase(PG8_LAS unsigned char* lds, const Gemm g, const Sched& S, const Epi& E) {
;     ...
;             PG8_WAIT_V(8); PG8_WAIT_L(0); PG8_BAR; PG8_MMA(0, 0, At, B0); PG8_MMA(0, 1, At, B1); PG8_BAR; PG8_SCHED;
;             PG8_LDA(At, 1, 1); PG8_STAGE(PG8_SB(1, 0), b3, voffB); PG8_STAGE(PG8_SB(1, 1), b3 + hstep, voffB); PG8_STAGE(PG8_SA(1, 0), a3, voffA);
;             PG8_WAIT_V(8); PG8_WAIT_L(0); PG8_BAR; PG8_MMA(1, 0, At, B0); PG8_MMA(1, 1, At, B1); PG8_BAR; PG8_SCHED;
	s_setprio 3
	s_waitcnt lgkmcnt(0)
	v_mfma_f32_16x16x128_f8f6f4 v[158:161], v[2:9], v[200:207], v[158:161]
	v_mfma_f32_16x16x128_f8f6f4 v[154:157], v[10:17], v[200:207], v[154:157]
	v_mfma_f32_16x16x128_f8f6f4 v[142:145], v[2:9], v[208:215], v[142:145]
	v_mfma_f32_16x16x128_f8f6f4 v[138:141], v[10:17], v[208:215], v[138:141]
	v_mfma_f32_16x16x128_f8f6f4 v[126:129], v[2:9], v[218:225], v[126:129]
	v_mfma_f32_16x16x128_f8f6f4 v[122:125], v[10:17], v[218:225], v[122:125]
	v_mfma_f32_16x16x128_f8f6f4 v[110:113], v[2:9], v[226:233], v[110:113]
	v_mfma_f32_16x16x128_f8f6f4 v[106:109], v[10:17], v[226:233], v[106:109]
	s_setprio 0
	s_setprio 3
	v_mfma_f32_16x16x128_f8f6f4 v[150:153], v[18:25], v[200:207], v[150:153]
	v_mfma_f32_16x16x128_f8f6f4 v[146:149], v[26:33], v[200:207], v[146:149]
	v_mfma_f32_16x16x128_f8f6f4 v[134:137], v[18:25], v[208:215], v[134:137]
	v_mfma_f32_16x16x128_f8f6f4 v[130:133], v[26:33], v[208:215], v[130:133]
	v_mfma_f32_16x16x128_f8f6f4 v[118:121], v[18:25], v[218:225], v[118:121]
	v_mfma_f32_16x16x128_f8f6f4 v[114:117], v[26:33], v[218:225], v[114:117]
	v_mfma_f32_16x16x128_f8f6f4 v[102:105], v[18:25], v[226:233], v[102:105]
	v_mfma_f32_16x16x128_f8f6f4 v[98:101], v[26:33], v[226:233], v[98:101]
	s_setprio 0
	s_add_i32 s24, s36, s14
	s_mov_b32 m0, s24
	ds_read_b128 v[200:203], v197 offset:49152
	ds_read_b128 v[204:207], v197 offset:50176
	ds_read_b128 v[208:211], v197 offset:51200
	ds_read_b128 v[212:215], v197 offset:52224
	ds_read_b128 v[218:221], v197 offset:53248
	ds_read_b128 v[222:225], v197 offset:54272
	ds_read_b128 v[226:229], v197 offset:55296
	ds_read_b128 v[230:233], v197 offset:56320
	s_add_u32 s98, s74, 0x80
	s_addc_u32 s99, s75, 0
	global_load_lds_dwordx4 v166, s[98:99]
	s_add_i32 m0, s24, 0x2000
	s_add_u32 s24, s74, 0x40080
	s_addc_u32 s25, s75, 0
	s_add_i32 s36, s37, s14
	s_add_u32 s100, s74, 0x80
	s_addc_u32 s101, s75, 0
	global_load_lds_dwordx4 v170, s[100:101]
	s_mov_b32 m0, s36
	s_nop 0
	global_load_lds_dwordx4 v166, s[24:25]
	s_add_i32 m0, s36, 0x2000
	s_nop 0
	global_load_lds_dwordx4 v170, s[24:25]
	s_mov_b32 m0, s45
	s_nop 0
	s_add_u32 s98, s76, 0x80
	s_addc_u32 s99, s77, 0
	global_load_lds_dwordx4 v164, s[98:99]
	s_mov_b32 m0, s78
	s_nop 0
	s_add_u32 s100, s76, 0x80
	s_addc_u32 s101, s77, 0
	global_load_lds_dwordx4 v168, s[100:101]
	s_waitcnt vmcnt(8)
	s_waitcnt lgkmcnt(0)
	s_barrier
	s_setprio 3
	s_waitcnt lgkmcnt(0)
	v_mfma_f32_16x16x128_f8f6f4 v[94:97], v[2:9], v[200:207], v[94:97]
	v_mfma_f32_16x16x128_f8f6f4 v[90:93], v[10:17], v[200:207], v[90:93]
	v_mfma_f32_16x16x128_f8f6f4 v[78:81], v[2:9], v[208:215], v[78:81]
	v_mfma_f32_16x16x128_f8f6f4 v[74:77], v[10:17], v[208:215], v[74:77]
	v_mfma_f32_16x16x128_f8f6f4 v[62:65], v[2:9], v[218:225], v[62:65]
	v_mfma_f32_16x16x128_f8f6f4 v[58:61], v[10:17], v[218:225], v[58:61]
	v_mfma_f32_16x16x128_f8f6f4 v[46:49], v[2:9], v[226:233], v[46:49]
	v_mfma_f32_16x16x128_f8f6f4 v[42:45], v[10:17], v[226:233], v[42:45]
	s_setprio 0
	s_setprio 3
	v_mfma_f32_16x16x128_f8f6f4 v[86:89], v[18:25], v[200:207], v[86:89]
	v_mfma_f32_16x16x128_f8f6f4 v[82:85], v[26:33], v[200:207], v[82:85]
	v_mfma_f32_16x16x128_f8f6f4 v[70:73], v[18:25], v[208:215], v[70:73]
	v_mfma_f32_16x16x128_f8f6f4 v[66:69], v[26:33], v[208:215], v[66:69]
	v_mfma_f32_16x16x128_f8f6f4 v[54:57], v[18:25], v[218:225], v[54:57]
	v_mfma_f32_16x16x128_f8f6f4 v[50:53], v[26:33], v[218:225], v[50:53]
	v_mfma_f32_16x16x128_f8f6f4 v[38:41], v[18:25], v[226:233], v[38:41]
	v_mfma_f32_16x16x128_f8f6f4 v[34:37], v[26:33], v[226:233], v[34:37]
	s_setprio 0
	s_add_i32 s87, s87, 2
	s_add_u32 s72, s72, 0x100
	s_addc_u32 s73, s73, 0
	s_add_u32 s85, s85, 0x100
	s_addc_u32 s86, s86, 0
	s_cmp_gt_u32 s87, 13
	s_cbranch_scc0 .Lk1_Y
	s_branch .Lk1_exit
.Lk1_h1:
	s_cmp_lg_u64 s[8:9], 0
	s_cbranch_scc1 .Lk1_Y
; #define PG8_STAGE(bufoff, gbase, voff) do { _Pragma("unroll") for (int _i = 0; _i < 2; ++_i) \
;         __builtin_amdgcn_global_load_lds((const unsigned*)((const char*)(gbase) + (voff)[_i]), (PG8_LAS unsigned*)(lds + (bufoff) + ldsw + _i * 8192), 16, 0, 0); } while (0)
; #define PG8_LDA(dst, b, h) do { _Pragma("unroll") for (int m = 0; m < 4; ++m) _Pragma("unroll") for (int k = 0; k < 2; ++k) dst[m][k] = *(const PG8_LAS bf16x8*)(lds + PG8_SA(b, h) + aoff + m * 2048 + k * 1024); } while (0)
; #define PG8_LDB(dst, b, h) do { _Pragma("unroll") for (int n = 0; n < 2; ++n) _Pragma("unroll") for (int k = 0; k < 2; ++k) dst[n][k] = *(const PG8_LAS bf16x8*)(lds + PG8_SB(b, h) + boff + n * 2048 + k * 1024); } while (0)
; #define PG8_WAIT_V(n) asm volatile("s_waitcnt vmcnt(" #n ")" ::: "memory")
; #define PG8_WAIT_L(n) asm volatile("s_waitcnt lgkmcnt(" #n ")" ::: "memory")
; #define PG8_BAR __builtin_amdgcn_s_barrier()
; #define PG8_SCHED __builtin_amdgcn_sched_barrier(0)
; template <class Epi, class Sched, bool ALIGN_EPI = false, bool SP2 = false, bool F8 = false>
; __device__ __forceinline__ void gemm_phase(PG8_LAS unsigned char* lds, const Gemm g, const Sched& S, const Epi& E) {
;     ...
;             PG8_LDB(B0, 0, 0); PG8_LDB(B1, 0, 1); PG8_SCHED; PG8_LDA(At, 0, 0); PG8_STAGE(PG8_SA(1, 1), a1 + hstepA, voffA);
;             PG8_WAIT_V(8); PG8_WAIT_L(0); PG8_BAR; PG8_MMA(0, 0, At, B0); PG8_MMA(0, 1, At, B1); PG8_BAR; PG8_SCHED;
;             PG8_LDA(At, 0, 1); PG8_STAGE(PG8_SB(0, 0), b2, voffB); PG8_STAGE(PG8_SB(0, 1), b2 + hstep, voffB); PG8_STAGE(PG8_SA(0, 0), a2, voffA);
;             PG8_WAIT_V(8); PG8_WAIT_L(0); PG8_BAR; PG8_MMA(1, 0, At, B0); PG8_MMA(1, 1, At, B1); PG8_BAR; PG8_SCHED;
;             PG8_LDB(B0, 1, 0); PG8_LDB(B1, 1, 1); PG8_SCHED; PG8_LDA(At, 1, 0); PG8_STAGE(PG8_SA(0, 1), a2 + hstepA, voffA);
;             PG8_WAIT_V(8); PG8_WAIT_L(0); PG8_BAR; PG8_MMA(0, 0, At, B0); PG8_MMA(0, 1, At, B1); PG8_BAR; PG8_SCHED;
;             PG8_LDA(At, 1, 1); PG8_STAGE(PG8_SB(1, 0), b3, voffB); PG8_STAGE(PG8_SB(1, 1), b3 + hstep, voffB); PG8_STAGE(PG8_SA(1, 0), a3, voffA);
;             PG8_WAIT_V(8); PG8_WAIT_L(0); PG8_BAR; PG8_MMA(1, 0, At, B0); PG8_MMA(1, 1, At, B1); PG8_BAR; PG8_SCHED;
.Lk1_Xi:
	s_add_u32 s24, s72, 0xfffc0080
	s_addc_u32 s25, s73, -1
	s_cmp_eq_u32 s87, 12
	s_cselect_b32 s77, s7, s25
	s_cselect_b32 s76, s65, s24
	s_cselect_b32 s75, s63, s86
	s_cselect_b32 s74, s71, s85
	s_add_i32 m0, s26, 0xc000
	s_nop 0
	global_load_lds_dwordx4 v178, s[72:73]
	s_add_i32 m0, s26, 0xe000
	s_nop 0
	global_load_lds_dwordx4 v180, s[72:73]
	s_waitcnt vmcnt(8)
	s_waitcnt lgkmcnt(0)
	s_waitcnt lgkmcnt(0)
	s_barrier
	s_add_i32 s24, s81, s14
	s_mov_b32 m0, s24
	s_nop 0
	global_load_lds_dwordx4 v166, s[74:75]
	s_add_i32 m0, s24, 0x2000
	s_add_u32 s24, s74, 0x40000
	s_addc_u32 s25, s75, 0
	s_add_i32 s36, s82, s14
	global_load_lds_dwordx4 v170, s[74:75]
	s_mov_b32 m0, s36
	s_nop 0
	global_load_lds_dwordx4 v166, s[24:25]
	s_add_i32 m0, s36, 0x2000
	s_nop 0
	global_load_lds_dwordx4 v170, s[24:25]
	s_mov_b32 m0, s26
	s_nop 0
	global_load_lds_dwordx4 v164, s[76:77]
	s_mov_b32 m0, s27
	s_nop 0
	global_load_lds_dwordx4 v168, s[76:77]
	s_waitcnt vmcnt(8)
	s_waitcnt lgkmcnt(0)
	s_waitcnt lgkmcnt(0)
	s_barrier
	s_add_i32 s36, 0, 0x18000
	s_add_i32 s37, 0, 0x1c000
	v_add_u32_e32 v14, s36, v190
	v_add_u32_e32 v30, s37, v190
	s_add_u32 s24, s76, 0x40000
	s_addc_u32 s25, s77, 0
	s_mov_b32 m0, s28
	s_nop 0
	global_load_lds_dwordx4 v164, s[24:25]
	s_mov_b32 m0, s29
	s_nop 0
	global_load_lds_dwordx4 v168, s[24:25]
	s_waitcnt vmcnt(8)
	s_waitcnt lgkmcnt(0)
	s_waitcnt lgkmcnt(0)
	s_barrier
	s_add_i32 s24, s36, s14
	s_mov_b32 m0, s24
	s_add_u32 s98, s74, 0x80
	s_addc_u32 s99, s75, 0
	global_load_lds_dwordx4 v166, s[98:99]
	s_add_i32 m0, s24, 0x2000
	s_add_u32 s24, s74, 0x40080
	s_addc_u32 s25, s75, 0
	s_add_i32 s36, s37, s14
	s_add_u32 s100, s74, 0x80
	s_addc_u32 s101, s75, 0
	global_load_lds_dwordx4 v170, s[100:101]
	s_mov_b32 m0, s36
	s_nop 0
	global_load_lds_dwordx4 v166, s[24:25]
	s_add_i32 m0, s36, 0x2000
	s_nop 0
	global_load_lds_dwordx4 v170, s[24:25]
	s_mov_b32 m0, s45
	s_nop 0
	s_add_u32 s98, s76, 0x80
	s_addc_u32 s99, s77, 0
	global_load_lds_dwordx4 v164, s[98:99]
	s_mov_b32 m0, s78
	s_nop 0
	s_add_u32 s100, s76, 0x80
	s_addc_u32 s101, s77, 0
	global_load_lds_dwordx4 v168, s[100:101]
	s_waitcnt vmcnt(8)
	s_waitcnt lgkmcnt(0)
	s_waitcnt lgkmcnt(0)
	s_barrier
	s_add_i32 s87, s87, 2
	s_add_u32 s72, s72, 0x100
	s_addc_u32 s73, s73, 0
	s_add_u32 s85, s85, 0x100
	s_addc_u32 s86, s86, 0
	s_cmp_gt_u32 s87, 13
	s_cbranch_scc0 .Lk1_Xi
	s_branch .Lk1_exit_idle
.Lk1_Yi:
	s_add_u32 s24, s72, 0xfffc0080
	s_addc_u32 s25, s73, -1
	s_cmp_eq_u32 s87, 12
	s_cselect_b32 s77, s7, s25
	s_cselect_b32 s76, s65, s24
	s_cselect_b32 s75, s63, s86
	s_cselect_b32 s74, s71, s85
	s_add_i32 m0, s26, 0xc000
	s_nop 0
	global_load_lds_dwordx4 v178, s[72:73]
	s_add_i32 m0, s26, 0xe000
	s_nop 0
	global_load_lds_dwordx4 v180, s[72:73]
	s_waitcnt vmcnt(8)
	s_waitcnt lgkmcnt(0)
	s_barrier
	s_waitcnt lgkmcnt(0)
	s_add_i32 s24, s81, s14
	s_mov_b32 m0, s24
	s_nop 0
	global_load_lds_dwordx4 v166, s[74:75]
	s_add_i32 m0, s24, 0x2000
	s_add_u32 s24, s74, 0x40000
	s_addc_u32 s25, s75, 0
	s_add_i32 s36, s82, s14
	global_load_lds_dwordx4 v170, s[74:75]
	s_mov_b32 m0, s36
	s_nop 0
	global_load_lds_dwordx4 v166, s[24:25]
	s_add_i32 m0, s36, 0x2000
	s_nop 0
	global_load_lds_dwordx4 v170, s[24:25]
	s_mov_b32 m0, s26
	s_nop 0
	global_load_lds_dwordx4 v164, s[76:77]
	s_mov_b32 m0, s27
	s_nop 0
	global_load_lds_dwordx4 v168, s[76:77]
	s_waitcnt vmcnt(8)
	s_waitcnt lgkmcnt(0)
	s_barrier
	s_waitcnt lgkmcnt(0)
	s_add_i32 s36, 0, 0x18000
	s_add_i32 s37, 0, 0x1c000
	v_add_u32_e32 v14, s36, v190
	v_add_u32_e32 v30, s37, v190
	s_add_u32 s24, s76, 0x40000
	s_addc_u32 s25, s77, 0
	s_mov_b32 m0, s28
	s_nop 0
	global_load_lds_dwordx4 v164, s[24:25]
	s_mov_b32 m0, s29
	s_nop 0
	global_load_lds_dwordx4 v168, s[24:25]
	s_waitcnt vmcnt(8)
	s_waitcnt lgkmcnt(0)
	s_barrier
	s_waitcnt lgkmcnt(0)
	s_add_i32 s24, s36, s14
	s_mov_b32 m0, s24
	s_add_u32 s98, s74, 0x80
	s_addc_u32 s99, s75, 0
	global_load_lds_dwordx4 v166, s[98:99]
	s_add_i32 m0, s24, 0x2000
	s_add_u32 s24, s74, 0x40080
	s_addc_u32 s25, s75, 0
	s_add_i32 s36, s37, s14
	s_add_u32 s100, s74, 0x80
	s_addc_u32 s101, s75, 0
	global_load_lds_dwordx4 v170, s[100:101]
	s_mov_b32 m0, s36
	s_nop 0
	global_load_lds_dwordx4 v166, s[24:25]
	s_add_i32 m0, s36, 0x2000
	s_nop 0
	global_load_lds_dwordx4 v170, s[24:25]
	s_mov_b32 m0, s45
	s_nop 0
	s_add_u32 s98, s76, 0x80
	s_addc_u32 s99, s77, 0
	global_load_lds_dwordx4 v164, s[98:99]
	s_mov_b32 m0, s78
	s_nop 0
	s_add_u32 s100, s76, 0x80
	s_addc_u32 s101, s77, 0
	global_load_lds_dwordx4 v168, s[100:101]
	s_waitcnt vmcnt(8)
	s_waitcnt lgkmcnt(0)
	s_barrier
	s_waitcnt lgkmcnt(0)
	s_add_i32 s87, s87, 2
	s_add_u32 s72, s72, 0x100
	s_addc_u32 s73, s73, 0
	s_add_u32 s85, s85, 0x100
	s_addc_u32 s86, s86, 0
	s_cmp_gt_u32 s87, 13
	s_cbranch_scc0 .Lk1_Yi
.Lk1_exit_idle:
	s_andn2_b64 vcc, exec, s[54:55]
	s_mov_b64 s[6:7], -1
	s_cbranch_vccnz .LBB0_283
	s_branch .LBB0_282

; #define GAS __attribute__((address_space(1)))
; #define LAS __attribute__((address_space(3)))
; __global__ void __launch_bounds__(NTHR, 2) fwd_kernel(Args args) {
;     ...
;             constexpr int NCTXU = (MC / 256) * (2 * RW / 256);
;             LAS float* sh2T = (LAS float*)lds;
;             __syncthreads();
;             for (int i = tid; i < 2 * D / 4; i += NTHR) { const int r = i / (D / 4), k = 4 * (i % (D / 4)); *(LAS f32x4*)(sh2T + r * D + k) = *(const f32x4*)(MODF + (size_t)r * NMOD + 3 * D + k); }
;             __syncthreads();
;             const bool tailw = G > NCTXU; const int tw = tailw ? (bx - NCTXU) * NWAVES + wave : gw, ntw = tailw ? (G - NCTXU) * NWAVES : NGW;
;             if (!tailw || bx >= NCTXU)
;             for (int col = tw; col < NUP; col += 2 * ntw) {
;                 const int col2 = col + ntw < NUP ? col + ntw : col;
;                 const bf16* wr0 = WUP_T + (size_t)col * D; const bf16* wr1 = WUP_T + (size_t)col2 * D; float s0 = 0.f, s1 = 0.f, t0 = 0.f, t1 = 0.f; v4u wq0[4], wq1[4];
; #pragma unroll
;                 for (int j = 0; j < 4; ++j) { const int k0 = 8 * (lane + 64 * j); wq0[j] = *(const GAS v4u*)(wr0 + k0); wq1[j] = *(const GAS v4u*)(wr1 + k0); }
; #pragma unroll
;                 for (int j = 0; j < 4; ++j) { const int k0 = 8 * (lane + 64 * j);
;                     const f32x4 a0 = *(const LAS f32x4*)(sh2T + k0), a1 = *(const LAS f32x4*)(sh2T + k0 + 4), c0 = *(const LAS f32x4*)(sh2T + D + k0), c1 = *(const LAS f32x4*)(sh2T + D + k0 + 4);
.LBB0_315:
	v_and_b32_e32 v10, 0x7fc, v6
	v_mul_u32_u24_e32 v2, 0x3000, v7
	v_lshl_add_u64 v[8:9], v[2:3], 2, s[60:61]
	v_lshlrev_b32_e32 v2, 2, v10
	v_lshl_add_u64 v[8:9], v[8:9], 0, v[2:3]
	v_add_co_u32_e32 v8, vcc, 0x6000, v8
	v_add_u32_e32 v7, 1, v7
	s_nop 0
	v_addc_co_u32_e32 v9, vcc, 0, v9, vcc
	global_load_dwordx4 v[8:11], v[8:9], off
	v_add_co_u32_e32 v4, vcc, 0x200, v4
	s_xor_b64 s[6:7], vcc, -1
	s_and_b64 s[6:7], exec, s[6:7]
	v_add_u32_e32 v6, 0x800, v6
	s_or_b64 s[4:5], s[6:7], s[4:5]
	s_waitcnt vmcnt(0)
	ds_write_b128 v5, v[8:11]
	v_add_u32_e32 v5, 0x2000, v5
	s_andn2_b64 exec, exec, s[4:5]
	s_cbranch_execnz .LBB0_315
	s_or_b64 exec, exec, s[4:5]
	s_add_i32 s8, s20, 0xffffff00
	s_add_i32 s9, s22, 0xffffff00
	s_cmp_lt_i32 s90, 33
	s_cselect_b64 s[4:5], -1, 0
	s_and_b64 s[6:7], s[4:5], exec
	s_cselect_b32 s15, s20, s8
	s_cselect_b32 s23, s22, s9
	s_cmp_gt_i32 s2, 31
	s_cselect_b64 s[6:7], -1, 0
	s_or_b64 s[4:5], s[6:7], s[4:5]
	s_cmpk_lt_i32 s15, 0x2c00
	s_cselect_b64 s[6:7], -1, 0
	s_and_b64 s[6:7], s[4:5], s[6:7]
	s_andn2_b64 vcc, exec, s[6:7]
	s_waitcnt lgkmcnt(0)
	s_barrier
	s_cbranch_vccnz .LBB0_321
	v_mbcnt_lo_u32_b32 v2, -1, 0
	v_mbcnt_hi_u32_b32 v2, -1, v2
	v_and_b32_e32 v3, 64, v2
	v_add_u32_e32 v3, 64, v3
	v_xor_b32_e32 v4, 1, v2
	v_cmp_lt_i32_e32 vcc, v4, v3
	v_lshl_add_u32 v62, v216, 5, 0
	v_lshlrev_b32_e32 v78, 4, v216
	v_cndmask_b32_e32 v4, v2, v4, vcc
	v_lshlrev_b32_e32 v82, 2, v4
	v_xor_b32_e32 v4, 2, v2
	v_cmp_lt_i32_e32 vcc, v4, v3
	v_mov_b32_e32 v79, 0
	v_lshl_add_u64 v[80:81], s[42:43], 0, v[78:79]
	v_cndmask_b32_e32 v4, v2, v4, vcc
	v_lshlrev_b32_e32 v83, 2, v4
	v_xor_b32_e32 v4, 4, v2
	v_cmp_lt_i32_e32 vcc, v4, v3
	v_mov_b32_e32 v78, 0xb000
	s_mov_b32 s6, s15
	v_cndmask_b32_e32 v4, v2, v4, vcc
	v_lshlrev_b32_e32 v84, 2, v4
	v_xor_b32_e32 v4, 8, v2
	v_cmp_lt_i32_e32 vcc, v4, v3
	s_nop 1
	v_cndmask_b32_e32 v4, v2, v4, vcc
	v_lshlrev_b32_e32 v85, 2, v4
	v_xor_b32_e32 v4, 16, v2
	v_cmp_lt_i32_e32 vcc, v4, v3
	s_nop 1
	v_cndmask_b32_e32 v4, v2, v4, vcc
	v_lshlrev_b32_e32 v86, 2, v4
	v_xor_b32_e32 v4, 32, v2
	v_cmp_lt_i32_e32 vcc, v4, v3
	s_nop 1
	v_cndmask_b32_e32 v2, v2, v4, vcc
	v_lshlrev_b32_e32 v87, 2, v2
	ds_read_b128 v[2:5], v62
	ds_read_b128 v[6:9], v62 offset:16
	ds_read_b128 v[10:13], v62 offset:8192
	ds_read_b128 v[14:17], v62 offset:8208
	ds_read_b128 v[18:21], v62 offset:2048
	ds_read_b128 v[22:25], v62 offset:2064
	ds_read_b128 v[26:29], v62 offset:10240
	ds_read_b128 v[30:33], v62 offset:10256
	ds_read_b128 v[34:37], v62 offset:4096
	ds_read_b128 v[38:41], v62 offset:4112
	ds_read_b128 v[42:45], v62 offset:12288
	ds_read_b128 v[46:49], v62 offset:12304
	ds_read_b128 v[50:53], v62 offset:6144
	ds_read_b128 v[54:57], v62 offset:6160
	ds_read_b128 v[58:61], v62 offset:14336
	ds_read_b128 v[62:65], v62 offset:14352
	v_cmp_eq_u32_e32 vcc, 0, v216
	s_branch .LBB0_319
